# opt26: last GEMM's epilogue (f32 out = residual + acc) with the residual pieces requested four row groups ahead and counted waits instead of vmcnt(0) after every piece; on v067
# speedup vs baseline: 1.0066x; 1.0026x over previous
.LBB0_2177:
	v_lshl_add_u32 v148, s12, 8, v150
	v_lshl_or_b32 v146, s13, 8, v152
	v_ashrrev_i32_e32 v149, 31, v148
	v_ashrrev_i32_e32 v147, 31, v146
	v_lshlrev_b64 v[144:145], 10, v[148:149]
	v_lshl_add_u64 v[144:145], v[144:145], 0, v[146:147]
	v_lshlrev_b64 v[160:161], 1, v[144:145]
	v_lshl_add_u64 v[156:157], s[14:15], 0, v[160:161]
	v_mov_b32_e32 v232, v156
	v_mov_b32_e32 v233, v157
	v_lshl_add_u64 v[234:235], v[144:145], 2, s[68:69]
	global_load_dwordx4 v[188:191], v[232:233], off
	global_load_dwordx4 v[192:195], v[232:233], off offset:256
	s_mov_b64 s[100:101], 0x8000
	v_lshl_add_u64 v[230:231], v[232:233], 0, s[100:101]
	global_load_dwordx4 v[196:199], v[230:231], off
	global_load_dwordx4 v[200:203], v[230:231], off offset:256
	s_mov_b64 s[100:101], 0x10000
	v_lshl_add_u64 v[230:231], v[232:233], 0, s[100:101]
	global_load_dwordx4 v[204:207], v[230:231], off
	global_load_dwordx4 v[208:211], v[230:231], off offset:256
	s_mov_b64 s[100:101], 0x18000
	v_lshl_add_u64 v[230:231], v[232:233], 0, s[100:101]
	global_load_dwordx4 v[212:215], v[230:231], off
	global_load_dwordx4 v[216:219], v[230:231], off offset:256
	s_waitcnt vmcnt(7)
	v_lshlrev_b32_e32 v166, 16, v188
	v_and_b32_e32 v167, 0xffff0000, v188
	v_lshlrev_b32_e32 v168, 16, v189
	v_and_b32_e32 v169, 0xffff0000, v189
	v_lshlrev_b32_e32 v170, 16, v190
	v_and_b32_e32 v171, 0xffff0000, v190
	v_lshlrev_b32_e32 v172, 16, v191
	v_and_b32_e32 v173, 0xffff0000, v191
	v_pk_add_f32 v[124:125], v[124:125], v[166:167]
	v_pk_add_f32 v[126:127], v[126:127], v[168:169]
	v_pk_add_f32 v[120:121], v[120:121], v[170:171]
	v_pk_add_f32 v[122:123], v[122:123], v[172:173]
	global_store_dwordx4 v[234:235], v[124:127], off
	global_store_dwordx4 v[234:235], v[120:123], off offset:16
	s_waitcnt vmcnt(8)
	v_lshlrev_b32_e32 v166, 16, v192
	v_and_b32_e32 v167, 0xffff0000, v192
	v_lshlrev_b32_e32 v168, 16, v193
	v_and_b32_e32 v169, 0xffff0000, v193
	v_lshlrev_b32_e32 v170, 16, v194
	v_and_b32_e32 v171, 0xffff0000, v194
	v_lshlrev_b32_e32 v172, 16, v195
	v_and_b32_e32 v173, 0xffff0000, v195
	v_pk_add_f32 v[116:117], v[116:117], v[166:167]
	v_pk_add_f32 v[118:119], v[118:119], v[168:169]
	v_pk_add_f32 v[112:113], v[112:113], v[170:171]
	v_pk_add_f32 v[114:115], v[114:115], v[172:173]
	global_store_dwordx4 v[234:235], v[116:119], off offset:512
	global_store_dwordx4 v[234:235], v[112:115], off offset:528
	s_mov_b64 s[100:101], 0x40000
	v_lshl_add_u64 v[230:231], v[232:233], 0, s[100:101]
	global_load_dwordx4 v[188:191], v[230:231], off
	global_load_dwordx4 v[192:195], v[230:231], off offset:256
	s_mov_b64 s[100:101], 0x10000
	v_lshl_add_u64 v[186:187], v[234:235], 0, s[100:101]
	s_waitcnt vmcnt(11)
	v_lshlrev_b32_e32 v166, 16, v196
	v_and_b32_e32 v167, 0xffff0000, v196
	v_lshlrev_b32_e32 v168, 16, v197
	v_and_b32_e32 v169, 0xffff0000, v197
	v_lshlrev_b32_e32 v170, 16, v198
	v_and_b32_e32 v171, 0xffff0000, v198
	v_lshlrev_b32_e32 v172, 16, v199
	v_and_b32_e32 v173, 0xffff0000, v199
	v_pk_add_f32 v[108:109], v[108:109], v[166:167]
	v_pk_add_f32 v[110:111], v[110:111], v[168:169]
	v_pk_add_f32 v[104:105], v[104:105], v[170:171]
	v_pk_add_f32 v[106:107], v[106:107], v[172:173]
	global_store_dwordx4 v[186:187], v[108:111], off
	global_store_dwordx4 v[186:187], v[104:107], off offset:16
	s_waitcnt vmcnt(12)
	v_lshlrev_b32_e32 v166, 16, v200
	v_and_b32_e32 v167, 0xffff0000, v200
	v_lshlrev_b32_e32 v168, 16, v201
	v_and_b32_e32 v169, 0xffff0000, v201
	v_lshlrev_b32_e32 v170, 16, v202
	v_and_b32_e32 v171, 0xffff0000, v202
	v_lshlrev_b32_e32 v172, 16, v203
	v_and_b32_e32 v173, 0xffff0000, v203
	v_pk_add_f32 v[100:101], v[100:101], v[166:167]
	v_pk_add_f32 v[102:103], v[102:103], v[168:169]
	v_pk_add_f32 v[96:97], v[96:97], v[170:171]
	v_pk_add_f32 v[98:99], v[98:99], v[172:173]
	global_store_dwordx4 v[186:187], v[100:103], off offset:512
	global_store_dwordx4 v[186:187], v[96:99], off offset:528
	s_mov_b64 s[100:101], 0x48000
	v_lshl_add_u64 v[230:231], v[232:233], 0, s[100:101]
	global_load_dwordx4 v[196:199], v[230:231], off
	global_load_dwordx4 v[200:203], v[230:231], off offset:256
	s_mov_b64 s[100:101], 0x20000
	v_lshl_add_u64 v[186:187], v[234:235], 0, s[100:101]
	s_waitcnt vmcnt(15)
	v_lshlrev_b32_e32 v166, 16, v204
	v_and_b32_e32 v167, 0xffff0000, v204
	v_lshlrev_b32_e32 v168, 16, v205
	v_and_b32_e32 v169, 0xffff0000, v205
	v_lshlrev_b32_e32 v170, 16, v206
	v_and_b32_e32 v171, 0xffff0000, v206
	v_lshlrev_b32_e32 v172, 16, v207
	v_and_b32_e32 v173, 0xffff0000, v207
	v_pk_add_f32 v[92:93], v[92:93], v[166:167]
	v_pk_add_f32 v[94:95], v[94:95], v[168:169]
	v_pk_add_f32 v[88:89], v[88:89], v[170:171]
	v_pk_add_f32 v[90:91], v[90:91], v[172:173]
	global_store_dwordx4 v[186:187], v[92:95], off
	global_store_dwordx4 v[186:187], v[88:91], off offset:16
	s_waitcnt vmcnt(16)
	v_lshlrev_b32_e32 v166, 16, v208
	v_and_b32_e32 v167, 0xffff0000, v208
	v_lshlrev_b32_e32 v168, 16, v209
	v_and_b32_e32 v169, 0xffff0000, v209
	v_lshlrev_b32_e32 v170, 16, v210
	v_and_b32_e32 v171, 0xffff0000, v210
	v_lshlrev_b32_e32 v172, 16, v211
	v_and_b32_e32 v173, 0xffff0000, v211
	v_pk_add_f32 v[84:85], v[84:85], v[166:167]
	v_pk_add_f32 v[86:87], v[86:87], v[168:169]
	v_pk_add_f32 v[80:81], v[80:81], v[170:171]
	v_pk_add_f32 v[82:83], v[82:83], v[172:173]
	global_store_dwordx4 v[186:187], v[84:87], off offset:512
	global_store_dwordx4 v[186:187], v[80:83], off offset:528
	s_mov_b64 s[100:101], 0x50000
	v_lshl_add_u64 v[230:231], v[232:233], 0, s[100:101]
	global_load_dwordx4 v[204:207], v[230:231], off
	global_load_dwordx4 v[208:211], v[230:231], off offset:256
	s_mov_b64 s[100:101], 0x30000
	v_lshl_add_u64 v[186:187], v[234:235], 0, s[100:101]
	s_waitcnt vmcnt(19)
	v_lshlrev_b32_e32 v166, 16, v212
	v_and_b32_e32 v167, 0xffff0000, v212
	v_lshlrev_b32_e32 v168, 16, v213
	v_and_b32_e32 v169, 0xffff0000, v213
	v_lshlrev_b32_e32 v170, 16, v214
	v_and_b32_e32 v171, 0xffff0000, v214
	v_lshlrev_b32_e32 v172, 16, v215
	v_and_b32_e32 v173, 0xffff0000, v215
	v_pk_add_f32 v[76:77], v[76:77], v[166:167]
	v_pk_add_f32 v[78:79], v[78:79], v[168:169]
	v_pk_add_f32 v[72:73], v[72:73], v[170:171]
	v_pk_add_f32 v[74:75], v[74:75], v[172:173]
	global_store_dwordx4 v[186:187], v[76:79], off
	global_store_dwordx4 v[186:187], v[72:75], off offset:16
	s_waitcnt vmcnt(20)
	v_lshlrev_b32_e32 v166, 16, v216
	v_and_b32_e32 v167, 0xffff0000, v216
	v_lshlrev_b32_e32 v168, 16, v217
	v_and_b32_e32 v169, 0xffff0000, v217
	v_lshlrev_b32_e32 v170, 16, v218
	v_and_b32_e32 v171, 0xffff0000, v218
	v_lshlrev_b32_e32 v172, 16, v219
	v_and_b32_e32 v173, 0xffff0000, v219
	v_pk_add_f32 v[68:69], v[68:69], v[166:167]
	v_pk_add_f32 v[70:71], v[70:71], v[168:169]
	v_pk_add_f32 v[64:65], v[64:65], v[170:171]
	v_pk_add_f32 v[66:67], v[66:67], v[172:173]
	global_store_dwordx4 v[186:187], v[68:71], off offset:512
	global_store_dwordx4 v[186:187], v[64:67], off offset:528
	s_mov_b64 s[100:101], 0x58000
	v_lshl_add_u64 v[230:231], v[232:233], 0, s[100:101]
	global_load_dwordx4 v[212:215], v[230:231], off
	global_load_dwordx4 v[216:219], v[230:231], off offset:256
	s_mov_b64 s[100:101], 0x80000
	v_lshl_add_u64 v[186:187], v[234:235], 0, s[100:101]
	s_waitcnt vmcnt(19)
	v_lshlrev_b32_e32 v166, 16, v188
	v_and_b32_e32 v167, 0xffff0000, v188
	v_lshlrev_b32_e32 v168, 16, v189
	v_and_b32_e32 v169, 0xffff0000, v189
	v_lshlrev_b32_e32 v170, 16, v190
	v_and_b32_e32 v171, 0xffff0000, v190
	v_lshlrev_b32_e32 v172, 16, v191
	v_and_b32_e32 v173, 0xffff0000, v191
	v_pk_add_f32 v[60:61], v[60:61], v[166:167]
	v_pk_add_f32 v[62:63], v[62:63], v[168:169]
	v_pk_add_f32 v[56:57], v[56:57], v[170:171]
	v_pk_add_f32 v[58:59], v[58:59], v[172:173]
	global_store_dwordx4 v[186:187], v[60:63], off
	global_store_dwordx4 v[186:187], v[56:59], off offset:16
	s_waitcnt vmcnt(20)
	v_lshlrev_b32_e32 v166, 16, v192
	v_and_b32_e32 v167, 0xffff0000, v192
	v_lshlrev_b32_e32 v168, 16, v193
	v_and_b32_e32 v169, 0xffff0000, v193
	v_lshlrev_b32_e32 v170, 16, v194
	v_and_b32_e32 v171, 0xffff0000, v194
	v_lshlrev_b32_e32 v172, 16, v195
	v_and_b32_e32 v173, 0xffff0000, v195
	v_pk_add_f32 v[52:53], v[52:53], v[166:167]
	v_pk_add_f32 v[54:55], v[54:55], v[168:169]
	v_pk_add_f32 v[48:49], v[48:49], v[170:171]
	v_pk_add_f32 v[50:51], v[50:51], v[172:173]
	global_store_dwordx4 v[186:187], v[52:55], off offset:512
	global_store_dwordx4 v[186:187], v[48:51], off offset:528
	s_mov_b64 s[100:101], 0x90000
	v_lshl_add_u64 v[186:187], v[234:235], 0, s[100:101]
	s_waitcnt vmcnt(17)
	v_lshlrev_b32_e32 v166, 16, v196
	v_and_b32_e32 v167, 0xffff0000, v196
	v_lshlrev_b32_e32 v168, 16, v197
	v_and_b32_e32 v169, 0xffff0000, v197
	v_lshlrev_b32_e32 v170, 16, v198
	v_and_b32_e32 v171, 0xffff0000, v198
	v_lshlrev_b32_e32 v172, 16, v199
	v_and_b32_e32 v173, 0xffff0000, v199
	v_pk_add_f32 v[44:45], v[44:45], v[166:167]
	v_pk_add_f32 v[46:47], v[46:47], v[168:169]
	v_pk_add_f32 v[40:41], v[40:41], v[170:171]
	v_pk_add_f32 v[42:43], v[42:43], v[172:173]
	global_store_dwordx4 v[186:187], v[44:47], off
	global_store_dwordx4 v[186:187], v[40:43], off offset:16
	s_waitcnt vmcnt(18)
	v_lshlrev_b32_e32 v166, 16, v200
	v_and_b32_e32 v167, 0xffff0000, v200
	v_lshlrev_b32_e32 v168, 16, v201
	v_and_b32_e32 v169, 0xffff0000, v201
	v_lshlrev_b32_e32 v170, 16, v202
	v_and_b32_e32 v171, 0xffff0000, v202
	v_lshlrev_b32_e32 v172, 16, v203
	v_and_b32_e32 v173, 0xffff0000, v203
	v_pk_add_f32 v[36:37], v[36:37], v[166:167]
	v_pk_add_f32 v[38:39], v[38:39], v[168:169]
	v_pk_add_f32 v[32:33], v[32:33], v[170:171]
	v_pk_add_f32 v[34:35], v[34:35], v[172:173]
	global_store_dwordx4 v[186:187], v[36:39], off offset:512
	global_store_dwordx4 v[186:187], v[32:35], off offset:528
	s_mov_b64 s[100:101], 0xa0000
	v_lshl_add_u64 v[186:187], v[234:235], 0, s[100:101]
	s_waitcnt vmcnt(15)
	v_lshlrev_b32_e32 v166, 16, v204
	v_and_b32_e32 v167, 0xffff0000, v204
	v_lshlrev_b32_e32 v168, 16, v205
	v_and_b32_e32 v169, 0xffff0000, v205
	v_lshlrev_b32_e32 v170, 16, v206
	v_and_b32_e32 v171, 0xffff0000, v206
	v_lshlrev_b32_e32 v172, 16, v207
	v_and_b32_e32 v173, 0xffff0000, v207
	v_pk_add_f32 v[28:29], v[28:29], v[166:167]
	v_pk_add_f32 v[30:31], v[30:31], v[168:169]
	v_pk_add_f32 v[24:25], v[24:25], v[170:171]
	v_pk_add_f32 v[26:27], v[26:27], v[172:173]
	global_store_dwordx4 v[186:187], v[28:31], off
	global_store_dwordx4 v[186:187], v[24:27], off offset:16
	s_waitcnt vmcnt(16)
	v_lshlrev_b32_e32 v166, 16, v208
	v_and_b32_e32 v167, 0xffff0000, v208
	v_lshlrev_b32_e32 v168, 16, v209
	v_and_b32_e32 v169, 0xffff0000, v209
	v_lshlrev_b32_e32 v170, 16, v210
	v_and_b32_e32 v171, 0xffff0000, v210
	v_lshlrev_b32_e32 v172, 16, v211
	v_and_b32_e32 v173, 0xffff0000, v211
	v_pk_add_f32 v[20:21], v[20:21], v[166:167]
	v_pk_add_f32 v[22:23], v[22:23], v[168:169]
	v_pk_add_f32 v[16:17], v[16:17], v[170:171]
	v_pk_add_f32 v[18:19], v[18:19], v[172:173]
	global_store_dwordx4 v[186:187], v[20:23], off offset:512
	global_store_dwordx4 v[186:187], v[16:19], off offset:528
	s_mov_b64 s[100:101], 0xb0000
	v_lshl_add_u64 v[186:187], v[234:235], 0, s[100:101]
	s_waitcnt vmcnt(13)
	v_lshlrev_b32_e32 v166, 16, v212
	v_and_b32_e32 v167, 0xffff0000, v212
	v_lshlrev_b32_e32 v168, 16, v213
	v_and_b32_e32 v169, 0xffff0000, v213
	v_lshlrev_b32_e32 v170, 16, v214
	v_and_b32_e32 v171, 0xffff0000, v214
	v_lshlrev_b32_e32 v172, 16, v215
	v_and_b32_e32 v173, 0xffff0000, v215
	v_pk_add_f32 v[12:13], v[12:13], v[166:167]
	v_pk_add_f32 v[14:15], v[14:15], v[168:169]
	v_pk_add_f32 v[8:9], v[8:9], v[170:171]
	v_pk_add_f32 v[10:11], v[10:11], v[172:173]
	global_store_dwordx4 v[186:187], v[12:15], off
	global_store_dwordx4 v[186:187], v[8:11], off offset:16
	s_waitcnt vmcnt(14)
	v_lshlrev_b32_e32 v166, 16, v216
	v_and_b32_e32 v167, 0xffff0000, v216
	v_lshlrev_b32_e32 v168, 16, v217
	v_and_b32_e32 v169, 0xffff0000, v217
	v_lshlrev_b32_e32 v170, 16, v218
	v_and_b32_e32 v171, 0xffff0000, v218
	v_lshlrev_b32_e32 v172, 16, v219
	v_and_b32_e32 v173, 0xffff0000, v219
	v_pk_add_f32 v[4:5], v[4:5], v[166:167]
	v_pk_add_f32 v[6:7], v[6:7], v[168:169]
	v_pk_add_f32 v[0:1], v[0:1], v[170:171]
	v_pk_add_f32 v[2:3], v[2:3], v[172:173]
	global_store_dwordx4 v[186:187], v[4:7], off offset:512
	global_store_dwordx4 v[186:187], v[0:3], off offset:528
	s_and_b64 vcc, exec, s[4:5]
	s_mov_b64 s[4:5], -1
	s_cbranch_vccnz .LBB0_2162
	s_andn2_b64 vcc, exec, s[6:7]
	s_cbranch_vccnz .LBB0_2161
	s_nop 0
	s_branch .LBB0_2161
